# P2b late-weight conversions moved off the 24 workgroups that own two V^T units
# speedup vs baseline: 1.0344x; 1.0018x over previous
.LBB0_382:
	v_and_b32_e32 v3, 15, v0
	v_lshrrev_b32_e32 v26, 4, v0
	v_lshlrev_b32_e32 v2, 2, v3
	v_mul_u32_u24_e32 v4, 0x414, v26
	v_lshlrev_b32_e32 v3, 4, v3
	v_add3_u32 v27, 0, v4, v3
	v_lshlrev_b32_e32 v3, 3, v0
	v_lshrrev_b32_e32 v28, 3, v0
	v_and_b32_e32 v4, 56, v3
	s_waitcnt lgkmcnt(0)
	s_add_u32 s4, s50, 0x2000000
	v_mul_u32_u24_e32 v3, 0x414, v4
	v_lshlrev_b32_e32 v5, 2, v28
	s_addc_u32 s5, s51, 0
	v_add3_u32 v30, 0, v3, v5
	v_lshrrev_b32_e32 v3, 2, v0
	v_or_b32_e32 v32, 64, v28
	s_load_dwordx2 s[18:19], s[96:97], 0xd0
	s_load_dwordx4 s[12:15], s[96:97], 0xc0
	s_load_dwordx2 s[20:21], s[96:97], 0x18
	v_mov_b32_e32 v7, 0
	v_and_b32_e32 v31, 0x78, v3
	v_lshlrev_b32_e32 v3, 1, v32
	v_or_b32_e32 v34, 0x80, v28
	s_add_u32 s6, s50, 0x1e00000
	v_lshlrev_b32_e32 v6, 1, v4
	v_and_b32_e32 v33, 0xf8, v3
	v_lshlrev_b32_e32 v3, 1, v34
	v_or_b32_e32 v36, 0xc0, v28
	s_addc_u32 s7, s51, 0
	v_lshl_add_u64 v[8:9], s[50:51], 0, v[6:7]
	s_mov_b64 s[0:1], 0x1a00000
	v_and_b32_e32 v35, 0x178, v3
	v_lshlrev_b32_e32 v3, 1, v36
	v_lshlrev_b32_e32 v14, 8, v28
	v_lshlrev_b32_e32 v16, 8, v32
	v_lshlrev_b32_e32 v18, 8, v34
	v_lshlrev_b32_e32 v20, 8, v36
	v_lshl_add_u64 v[10:11], v[8:9], 0, s[0:1]
	s_mov_b64 s[0:1], 0x1800000
	s_add_u32 s8, s50, 0x1200000
	s_mov_b32 s17, 0
	v_bfe_u32 v29, v0, 3, 2
	v_and_b32_e32 v37, 0x1f8, v3
	v_lshl_add_u64 v[12:13], v[8:9], 0, s[0:1]
	s_addc_u32 s9, s51, 0
	s_sub_i32 s3, s90, 24
	s_add_i32 s24, s2, 0xe8
	s_movk_i32 s25, 0x3ff
	s_mov_b64 s[22:23], 0x8000
	s_mov_b32 s26, 0x8000
	v_add_u32_e32 v38, 0x8280, v27
	v_add_u32_e32 v39, 0x8288, v27
	v_add_u32_e32 v40, 0x8380, v27
	v_add_u32_e32 v41, 0x8388, v27
	v_add_u32_e32 v42, 0x8480, v27
	v_add_u32_e32 v43, 0x8488, v27
	v_add_u32_e32 v44, 0x8580, v27
	v_add_u32_e32 v45, 0x8588, v27
	s_movk_i32 s27, 0x88
	v_lshlrev_b32_e32 v14, 1, v14
	v_lshlrev_b32_e32 v16, 1, v16
	v_lshlrev_b32_e32 v18, 1, v18
	v_lshlrev_b32_e32 v20, 1, v20
	s_mov_b64 s[42:43], 0x40000
	s_mov_b32 s29, 0x40000
	s_mov_b64 s[44:45], 0x20000
	s_mov_b32 s33, 0x20000
	s_mov_b32 s35, 0x9000
	v_lshlrev_b32_e32 v6, 2, v2
	v_lshlrev_b32_e32 v22, 1, v4
	v_mov_b32_e32 v46, 0x3d800000
	v_mov_b32_e32 v47, 0x800
	s_add_i32 s24, s2, 0xd0
	s_cmp_lt_u32 s2, 48
	s_cselect_b32 s24, 0x1000, s24
	s_add_i32 s39, s28, 0xffffffe8
	s_branch .Lp2b_chk

.LBB0_385:
	s_add_i32 s24, s24, 0xd0
	s_add_i32 s39, s39, 0xd0
.Lp2b_chk:
	s_add_i32 s0, s24, 0xffffff00
	s_cmpk_gt_i32 s0, 0x31f
	s_waitcnt lgkmcnt(0)
	s_cbranch_scc1 .LBB0_467
